# merge epilogue specialised into ratio/final variants with packed f32 multiplies and a load ring (lever 7: instruction selection)
# speedup vs baseline: 1.0236x; 1.0121x over previous
.LBB0_919:
	s_add_u32 s29, s24, s28
	s_addc_u32 s39, s25, 0
	s_add_u32 s34, s29, 0x100
	s_addc_u32 s35, s39, 0
	s_and_b64 s[30:31], s[26:27], exec
	s_cselect_b32 s35, s0, s35
	s_cselect_b32 s34, s97, s34
	s_add_u32 s28, s22, s28
	s_addc_u32 s30, s23, 0
	s_add_u32 s28, s28, 0x100
	s_addc_u32 s30, s30, 0
	s_and_b64 s[26:27], s[26:27], exec
	s_cselect_b32 s37, s6, s30
	s_cselect_b32 s36, s7, s28
	s_add_u32 s38, s29, 0x40080
	s_addc_u32 s39, s39, 0
	s_add_i32 m0, s66, 0xc000
	s_add_i32 vcc_lo, s66, 0xe000
	s_add_u32 s30, s36, 0x40000
	s_addc_u32 s31, s37, 0
	v_or_b32_e32 v128, 0x10000, v244
	v_add_u32_e32 v132, 0x10400, v244
	v_add_u32_e32 v136, 0x10800, v244
	v_add_u32_e32 v140, 0x10c00, v244
	s_add_u32 s28, s34, 0x40000
	ds_read_b128 v[128:131], v128
	ds_read_b128 v[132:135], v132
	ds_read_b128 v[136:139], v136
	ds_read_b128 v[140:143], v140
	s_addc_u32 s29, s35, 0
	s_add_u32 s26, s36, 0x40080
	s_addc_u32 s27, s37, 0
	v_lshl_add_u64 v[176:177], s[38:39], 0, v[206:207]
	ds_read_b128 v[144:147], v243
	ds_read_b128 v[148:151], v243 offset:1024
	ds_read_b128 v[152:155], v243 offset:2048
	ds_read_b128 v[156:159], v243 offset:3072
	ds_read_b128 v[160:163], v243 offset:4096
	ds_read_b128 v[164:167], v243 offset:5120
	ds_read_b128 v[168:171], v243 offset:6144
	ds_read_b128 v[172:175], v243 offset:7168
	global_load_lds_dwordx4 v[176:177], off
	v_lshl_add_u64 v[176:177], s[38:39], 0, v[210:211]
	s_mov_b32 m0, vcc_lo
	s_nop 0
	global_load_lds_dwordx4 v[176:177], off
	s_waitcnt lgkmcnt(8)
	s_barrier
	s_waitcnt lgkmcnt(0)
	s_setprio 1
	s_waitcnt lgkmcnt(0)
	v_mfma_f32_16x16x32_bf16 v[124:127], v[128:131], v[144:147], v[124:127]
	v_mfma_f32_16x16x32_bf16 v[120:123], v[136:139], v[144:147], v[120:123]
	v_mfma_f32_16x16x32_bf16 v[116:119], v[128:131], v[152:155], v[116:119]
	v_mfma_f32_16x16x32_bf16 v[112:115], v[136:139], v[152:155], v[112:115]
	v_mfma_f32_16x16x32_bf16 v[108:111], v[128:131], v[160:163], v[108:111]
	v_mfma_f32_16x16x32_bf16 v[104:107], v[136:139], v[160:163], v[104:107]
	v_mfma_f32_16x16x32_bf16 v[100:103], v[128:131], v[168:171], v[100:103]
	v_mfma_f32_16x16x32_bf16 v[96:99], v[136:139], v[168:171], v[96:99]
	v_mfma_f32_16x16x32_bf16 v[124:127], v[132:135], v[148:151], v[124:127]
	v_mfma_f32_16x16x32_bf16 v[120:123], v[140:143], v[148:151], v[120:123]
	v_mfma_f32_16x16x32_bf16 v[116:119], v[132:135], v[156:159], v[116:119]
	v_mfma_f32_16x16x32_bf16 v[112:115], v[140:143], v[156:159], v[112:115]
	v_mfma_f32_16x16x32_bf16 v[108:111], v[132:135], v[164:167], v[108:111]
	v_mfma_f32_16x16x32_bf16 v[104:107], v[140:143], v[164:167], v[104:107]
	v_mfma_f32_16x16x32_bf16 v[100:103], v[132:135], v[172:175], v[100:103]
	v_mfma_f32_16x16x32_bf16 v[96:99], v[140:143], v[172:175], v[96:99]
	s_setprio 0
	s_barrier
	s_mov_b32 m0, s13
	v_or_b32_e32 v176, 0x14000, v244
	v_add_u32_e32 v180, 0x14400, v244
	v_add_u32_e32 v184, 0x14800, v244
	v_add_u32_e32 v188, 0x14c00, v244
	v_lshl_add_u64 v[216:217], s[36:37], 0, v[208:209]
	ds_read_b128 v[176:179], v176
	ds_read_b128 v[180:183], v180
	ds_read_b128 v[184:187], v184
	ds_read_b128 v[188:191], v188
	global_load_lds_dwordx4 v[216:217], off
	v_lshl_add_u64 v[218:219], s[36:37], 0, v[212:213]
	s_mov_b32 m0, s67
	s_nop 0
	global_load_lds_dwordx4 v[218:219], off
	s_barrier
	s_waitcnt lgkmcnt(0)
	s_setprio 1
	s_waitcnt lgkmcnt(0)
	v_mfma_f32_16x16x32_bf16 v[92:95], v[176:179], v[144:147], v[92:95]
	v_mfma_f32_16x16x32_bf16 v[88:91], v[184:187], v[144:147], v[88:91]
	v_mfma_f32_16x16x32_bf16 v[84:87], v[176:179], v[152:155], v[84:87]
	v_mfma_f32_16x16x32_bf16 v[80:83], v[184:187], v[152:155], v[80:83]
	v_mfma_f32_16x16x32_bf16 v[76:79], v[176:179], v[160:163], v[76:79]
	v_mfma_f32_16x16x32_bf16 v[72:75], v[184:187], v[160:163], v[72:75]
	v_mfma_f32_16x16x32_bf16 v[68:71], v[176:179], v[168:171], v[68:71]
	v_mfma_f32_16x16x32_bf16 v[64:67], v[184:187], v[168:171], v[64:67]
	v_mfma_f32_16x16x32_bf16 v[92:95], v[180:183], v[148:151], v[92:95]
	v_mfma_f32_16x16x32_bf16 v[88:91], v[188:191], v[148:151], v[88:91]
	v_mfma_f32_16x16x32_bf16 v[84:87], v[180:183], v[156:159], v[84:87]
	v_mfma_f32_16x16x32_bf16 v[80:83], v[188:191], v[156:159], v[80:83]
	v_mfma_f32_16x16x32_bf16 v[76:79], v[180:183], v[164:167], v[76:79]
	v_mfma_f32_16x16x32_bf16 v[72:75], v[188:191], v[164:167], v[72:75]
	v_mfma_f32_16x16x32_bf16 v[68:71], v[180:183], v[172:175], v[68:71]
	v_mfma_f32_16x16x32_bf16 v[64:67], v[188:191], v[172:175], v[64:67]
	s_setprio 0
	s_mov_b32 m0, s66
	v_lshl_add_u64 v[246:247], s[34:35], 0, v[206:207]
	s_barrier
	ds_read_b128 v[144:147], v243 offset:16384
	ds_read_b128 v[148:151], v243 offset:17408
	ds_read_b128 v[152:155], v243 offset:18432
	ds_read_b128 v[156:159], v243 offset:19456
	ds_read_b128 v[160:163], v243 offset:20480
	ds_read_b128 v[164:167], v243 offset:21504
	ds_read_b128 v[168:171], v243 offset:22528
	ds_read_b128 v[172:175], v243 offset:23552
	global_load_lds_dwordx4 v[246:247], off
	v_lshl_add_u64 v[248:249], s[34:35], 0, v[210:211]
	s_mov_b32 m0, s68
	s_nop 0
	global_load_lds_dwordx4 v[248:249], off
	s_barrier
	s_waitcnt lgkmcnt(0)
	s_setprio 1
	s_waitcnt lgkmcnt(0)
	v_mfma_f32_16x16x32_bf16 v[60:63], v[128:131], v[144:147], v[60:63]
	v_mfma_f32_16x16x32_bf16 v[56:59], v[136:139], v[144:147], v[56:59]
	v_mfma_f32_16x16x32_bf16 v[52:55], v[128:131], v[152:155], v[52:55]
	v_mfma_f32_16x16x32_bf16 v[48:51], v[136:139], v[152:155], v[48:51]
	v_mfma_f32_16x16x32_bf16 v[44:47], v[128:131], v[160:163], v[44:47]
	v_mfma_f32_16x16x32_bf16 v[40:43], v[136:139], v[160:163], v[40:43]
	v_mfma_f32_16x16x32_bf16 v[36:39], v[128:131], v[168:171], v[36:39]
	v_mfma_f32_16x16x32_bf16 v[32:35], v[136:139], v[168:171], v[32:35]
	v_mfma_f32_16x16x32_bf16 v[60:63], v[132:135], v[148:151], v[60:63]
	v_mfma_f32_16x16x32_bf16 v[56:59], v[140:143], v[148:151], v[56:59]
	v_mfma_f32_16x16x32_bf16 v[52:55], v[132:135], v[156:159], v[52:55]
	v_mfma_f32_16x16x32_bf16 v[48:51], v[140:143], v[156:159], v[48:51]
	v_mfma_f32_16x16x32_bf16 v[44:47], v[132:135], v[164:167], v[44:47]
	v_mfma_f32_16x16x32_bf16 v[40:43], v[140:143], v[164:167], v[40:43]
	v_mfma_f32_16x16x32_bf16 v[36:39], v[132:135], v[172:175], v[36:39]
	v_mfma_f32_16x16x32_bf16 v[32:35], v[140:143], v[172:175], v[32:35]
	s_setprio 0
	s_barrier
	s_mov_b32 m0, s69
	v_lshl_add_u64 v[128:129], s[30:31], 0, v[208:209]
	global_load_lds_dwordx4 v[128:129], off
	v_lshl_add_u64 v[128:129], s[30:31], 0, v[212:213]
	s_mov_b32 m0, s70
	s_nop 0
	global_load_lds_dwordx4 v[128:129], off
	s_waitcnt vmcnt(6)
	s_barrier
	s_setprio 1
	v_mfma_f32_16x16x32_bf16 v[28:31], v[176:179], v[144:147], v[28:31]
	v_mfma_f32_16x16x32_bf16 v[24:27], v[184:187], v[144:147], v[24:27]
	v_mfma_f32_16x16x32_bf16 v[20:23], v[176:179], v[152:155], v[20:23]
	v_mfma_f32_16x16x32_bf16 v[16:19], v[184:187], v[152:155], v[16:19]
	v_mfma_f32_16x16x32_bf16 v[12:15], v[176:179], v[160:163], v[12:15]
	v_mfma_f32_16x16x32_bf16 v[8:11], v[184:187], v[160:163], v[8:11]
	v_mfma_f32_16x16x32_bf16 v[4:7], v[176:179], v[168:171], v[4:7]
	v_mfma_f32_16x16x32_bf16 v[0:3], v[184:187], v[168:171], v[0:3]
	v_mfma_f32_16x16x32_bf16 v[28:31], v[180:183], v[148:151], v[28:31]
	v_mfma_f32_16x16x32_bf16 v[24:27], v[188:191], v[148:151], v[24:27]
	v_mfma_f32_16x16x32_bf16 v[20:23], v[180:183], v[156:159], v[20:23]
	v_mfma_f32_16x16x32_bf16 v[16:19], v[188:191], v[156:159], v[16:19]
	v_mfma_f32_16x16x32_bf16 v[12:15], v[180:183], v[164:167], v[12:15]
	v_mfma_f32_16x16x32_bf16 v[8:11], v[188:191], v[164:167], v[8:11]
	v_mfma_f32_16x16x32_bf16 v[4:7], v[180:183], v[172:175], v[4:7]
	v_mfma_f32_16x16x32_bf16 v[0:3], v[188:191], v[172:175], v[0:3]
	s_setprio 0
	v_or_b32_e32 v128, 0x18000, v244
	v_add_u32_e32 v132, 0x18400, v244
	v_add_u32_e32 v136, 0x18800, v244
	v_add_u32_e32 v140, 0x18c00, v244
	s_barrier
	ds_read_b128 v[128:131], v128
	ds_read_b128 v[132:135], v132
	ds_read_b128 v[136:139], v136
	ds_read_b128 v[140:143], v140
	s_mov_b32 m0, s71
	v_lshl_add_u64 v[176:177], s[28:29], 0, v[206:207]
	ds_read_b128 v[144:147], v243 offset:32768
	ds_read_b128 v[148:151], v243 offset:33792
	ds_read_b128 v[152:155], v243 offset:34816
	ds_read_b128 v[156:159], v243 offset:35840
	ds_read_b128 v[160:163], v243 offset:36864
	ds_read_b128 v[164:167], v243 offset:37888
	ds_read_b128 v[168:171], v243 offset:38912
	ds_read_b128 v[172:175], v243 offset:39936
	global_load_lds_dwordx4 v[176:177], off
	v_lshl_add_u64 v[176:177], s[28:29], 0, v[210:211]
	s_mov_b32 m0, s74
	s_nop 0
	global_load_lds_dwordx4 v[176:177], off
	s_waitcnt lgkmcnt(8)
	s_barrier
	s_waitcnt lgkmcnt(0)
	s_setprio 1
	s_waitcnt lgkmcnt(0)
	v_mfma_f32_16x16x32_bf16 v[124:127], v[128:131], v[144:147], v[124:127]
	v_mfma_f32_16x16x32_bf16 v[120:123], v[136:139], v[144:147], v[120:123]
	v_mfma_f32_16x16x32_bf16 v[116:119], v[128:131], v[152:155], v[116:119]
	v_mfma_f32_16x16x32_bf16 v[112:115], v[136:139], v[152:155], v[112:115]
	v_mfma_f32_16x16x32_bf16 v[108:111], v[128:131], v[160:163], v[108:111]
	v_mfma_f32_16x16x32_bf16 v[104:107], v[136:139], v[160:163], v[104:107]
	v_mfma_f32_16x16x32_bf16 v[100:103], v[128:131], v[168:171], v[100:103]
	v_mfma_f32_16x16x32_bf16 v[96:99], v[136:139], v[168:171], v[96:99]
	v_mfma_f32_16x16x32_bf16 v[124:127], v[132:135], v[148:151], v[124:127]
	v_mfma_f32_16x16x32_bf16 v[120:123], v[140:143], v[148:151], v[120:123]
	v_mfma_f32_16x16x32_bf16 v[116:119], v[132:135], v[156:159], v[116:119]
	v_mfma_f32_16x16x32_bf16 v[112:115], v[140:143], v[156:159], v[112:115]
	v_mfma_f32_16x16x32_bf16 v[108:111], v[132:135], v[164:167], v[108:111]
	v_mfma_f32_16x16x32_bf16 v[104:107], v[140:143], v[164:167], v[104:107]
	v_mfma_f32_16x16x32_bf16 v[100:103], v[132:135], v[172:175], v[100:103]
	v_mfma_f32_16x16x32_bf16 v[96:99], v[140:143], v[172:175], v[96:99]
	s_setprio 0
	s_barrier
	s_mov_b32 m0, s75
	v_or_b32_e32 v176, 0x1c000, v244
	v_add_u32_e32 v180, 0x1c400, v244
	v_add_u32_e32 v184, 0x1c800, v244
	v_add_u32_e32 v188, 0x1cc00, v244
	v_lshl_add_u64 v[216:217], v[216:217], 0, s[94:95]
	ds_read_b128 v[176:179], v176
	ds_read_b128 v[180:183], v180
	ds_read_b128 v[184:187], v184
	ds_read_b128 v[188:191], v188
	global_load_lds_dwordx4 v[216:217], off
	v_lshl_add_u64 v[216:217], v[218:219], 0, s[94:95]
	s_mov_b32 m0, s76
	s_nop 0
	global_load_lds_dwordx4 v[216:217], off
	s_barrier
	s_waitcnt lgkmcnt(0)
	s_setprio 1
	s_waitcnt lgkmcnt(0)
	v_mfma_f32_16x16x32_bf16 v[92:95], v[176:179], v[144:147], v[92:95]
	v_mfma_f32_16x16x32_bf16 v[88:91], v[184:187], v[144:147], v[88:91]
	v_mfma_f32_16x16x32_bf16 v[84:87], v[176:179], v[152:155], v[84:87]
	v_mfma_f32_16x16x32_bf16 v[80:83], v[184:187], v[152:155], v[80:83]
	v_mfma_f32_16x16x32_bf16 v[76:79], v[176:179], v[160:163], v[76:79]
	v_mfma_f32_16x16x32_bf16 v[72:75], v[184:187], v[160:163], v[72:75]
	v_mfma_f32_16x16x32_bf16 v[68:71], v[176:179], v[168:171], v[68:71]
	v_mfma_f32_16x16x32_bf16 v[64:67], v[184:187], v[168:171], v[64:67]
	v_mfma_f32_16x16x32_bf16 v[92:95], v[180:183], v[148:151], v[92:95]
	v_mfma_f32_16x16x32_bf16 v[88:91], v[188:191], v[148:151], v[88:91]
	v_mfma_f32_16x16x32_bf16 v[84:87], v[180:183], v[156:159], v[84:87]
	v_mfma_f32_16x16x32_bf16 v[80:83], v[188:191], v[156:159], v[80:83]
	v_mfma_f32_16x16x32_bf16 v[76:79], v[180:183], v[164:167], v[76:79]
	v_mfma_f32_16x16x32_bf16 v[72:75], v[188:191], v[164:167], v[72:75]
	v_mfma_f32_16x16x32_bf16 v[68:71], v[180:183], v[172:175], v[68:71]
	v_mfma_f32_16x16x32_bf16 v[64:67], v[188:191], v[172:175], v[64:67]
	s_setprio 0
	s_mov_b32 m0, s77
	v_lshl_add_u64 v[216:217], v[246:247], 0, s[94:95]
	s_barrier
	ds_read_b128 v[144:147], v243 offset:49152
	ds_read_b128 v[148:151], v243 offset:50176
	ds_read_b128 v[152:155], v243 offset:51200
	ds_read_b128 v[156:159], v243 offset:52224
	ds_read_b128 v[160:163], v243 offset:53248
	ds_read_b128 v[164:167], v243 offset:54272
	ds_read_b128 v[168:171], v243 offset:55296
	ds_read_b128 v[172:175], v243 offset:56320
	global_load_lds_dwordx4 v[216:217], off
	v_lshl_add_u64 v[216:217], v[248:249], 0, s[94:95]
	s_mov_b32 m0, s78
	s_nop 0
	global_load_lds_dwordx4 v[216:217], off
	s_barrier
	s_waitcnt lgkmcnt(0)
	s_setprio 1
	s_waitcnt lgkmcnt(0)
	v_mfma_f32_16x16x32_bf16 v[60:63], v[128:131], v[144:147], v[60:63]
	v_mfma_f32_16x16x32_bf16 v[56:59], v[136:139], v[144:147], v[56:59]
	v_mfma_f32_16x16x32_bf16 v[52:55], v[128:131], v[152:155], v[52:55]
	v_mfma_f32_16x16x32_bf16 v[48:51], v[136:139], v[152:155], v[48:51]
	v_mfma_f32_16x16x32_bf16 v[44:47], v[128:131], v[160:163], v[44:47]
	v_mfma_f32_16x16x32_bf16 v[40:43], v[136:139], v[160:163], v[40:43]
	v_mfma_f32_16x16x32_bf16 v[36:39], v[128:131], v[168:171], v[36:39]
	v_mfma_f32_16x16x32_bf16 v[32:35], v[136:139], v[168:171], v[32:35]
	v_mfma_f32_16x16x32_bf16 v[60:63], v[132:135], v[148:151], v[60:63]
	v_mfma_f32_16x16x32_bf16 v[56:59], v[140:143], v[148:151], v[56:59]
	v_mfma_f32_16x16x32_bf16 v[52:55], v[132:135], v[156:159], v[52:55]
	v_mfma_f32_16x16x32_bf16 v[48:51], v[140:143], v[156:159], v[48:51]
	v_mfma_f32_16x16x32_bf16 v[44:47], v[132:135], v[164:167], v[44:47]
	v_mfma_f32_16x16x32_bf16 v[40:43], v[140:143], v[164:167], v[40:43]
	v_mfma_f32_16x16x32_bf16 v[36:39], v[132:135], v[172:175], v[36:39]
	v_mfma_f32_16x16x32_bf16 v[32:35], v[140:143], v[172:175], v[32:35]
	s_setprio 0
	s_barrier
	s_mov_b32 m0, s79
	v_lshl_add_u64 v[128:129], s[26:27], 0, v[208:209]
	global_load_lds_dwordx4 v[128:129], off
	v_lshl_add_u64 v[128:129], s[26:27], 0, v[212:213]
	s_mov_b32 m0, s80
	s_nop 0
	global_load_lds_dwordx4 v[128:129], off
	s_waitcnt vmcnt(6)
	s_barrier
	s_setprio 1
	v_mfma_f32_16x16x32_bf16 v[28:31], v[176:179], v[144:147], v[28:31]
	v_mfma_f32_16x16x32_bf16 v[24:27], v[184:187], v[144:147], v[24:27]
	v_mfma_f32_16x16x32_bf16 v[20:23], v[176:179], v[152:155], v[20:23]
	v_mfma_f32_16x16x32_bf16 v[16:19], v[184:187], v[152:155], v[16:19]
	v_mfma_f32_16x16x32_bf16 v[12:15], v[176:179], v[160:163], v[12:15]
	v_mfma_f32_16x16x32_bf16 v[8:11], v[184:187], v[160:163], v[8:11]
	v_mfma_f32_16x16x32_bf16 v[4:7], v[176:179], v[168:171], v[4:7]
	v_mfma_f32_16x16x32_bf16 v[0:3], v[184:187], v[168:171], v[0:3]
	v_mfma_f32_16x16x32_bf16 v[28:31], v[180:183], v[148:151], v[28:31]
	v_mfma_f32_16x16x32_bf16 v[24:27], v[188:191], v[148:151], v[24:27]
	v_mfma_f32_16x16x32_bf16 v[20:23], v[180:183], v[156:159], v[20:23]
	v_mfma_f32_16x16x32_bf16 v[16:19], v[188:191], v[156:159], v[16:19]
	v_mfma_f32_16x16x32_bf16 v[12:15], v[180:183], v[164:167], v[12:15]
	v_mfma_f32_16x16x32_bf16 v[8:11], v[188:191], v[164:167], v[8:11]
	v_mfma_f32_16x16x32_bf16 v[4:7], v[180:183], v[172:175], v[4:7]
	v_mfma_f32_16x16x32_bf16 v[0:3], v[188:191], v[172:175], v[0:3]
	s_setprio 0
	s_movk_i32 s28, 0x100
	s_andn2_b64 vcc, exec, s[2:3]
	s_mov_b64 s[26:27], -1
	s_mov_b64 s[2:3], 0
	s_barrier
	s_cbranch_vccz .LBB0_919
	s_cmp_eq_u32 s17, 3
	s_cselect_b64 s[22:23], -1, 0
	s_and_b64 s[2:3], s[22:23], exec
	s_cselect_b32 s0, 0, 0x10000
	s_lshl_b32 s2, s17, 16
	s_ashr_i32 s3, s2, 31
	v_lshl_add_u32 v128, s14, 8, v201
	v_lshl_add_u64 v[218:219], s[2:3], 1, v[214:215]
	v_ashrrev_i32_e32 v129, 31, v128
	v_readlane_b32 s2, v254, 25
	s_lshl_b32 s6, s12, 8
	v_lshlrev_b64 v[128:129], 11, v[128:129]
	v_readlane_b32 s3, v254, 26
	s_ashr_i32 s7, s6, 31
	s_lshl_b32 s0, s0, 1
	v_lshl_add_u64 v[128:129], s[2:3], 0, v[128:129]
	s_cmp_lg_u32 s17, 3
	v_lshl_add_u64 v[128:129], s[6:7], 1, v[128:129]
	s_mov_b32 s17, s1
	v_lshl_add_u64 v[128:129], v[128:129], 0, s[16:17]
	v_lshl_add_u64 v[216:217], v[128:129], 0, v[192:193]
	s_mov_b32 s36, s92
	s_and_b64 vcc, exec, s[22:23]
	s_cbranch_vccnz .Lmg_final
	s_mov_b32 s98, 0x0
	s_mov_b32 s99, 0
	v_lshl_add_u64 v[176:177], v[218:219], 0, s[98:99]
	v_lshl_add_u64 v[178:179], v[176:177], 0, s[0:1]
	global_load_dwordx4 v[128:131], v[176:177], off
	global_load_dwordx4 v[132:135], v[178:179], off
	global_load_dwordx4 v[136:139], v[176:177], off offset:256
	global_load_dwordx4 v[140:143], v[178:179], off offset:256
	s_mov_b32 s98, 0x2000
	s_mov_b32 s99, 0
	v_lshl_add_u64 v[176:177], v[218:219], 0, s[98:99]
	v_lshl_add_u64 v[178:179], v[176:177], 0, s[0:1]
	global_load_dwordx4 v[144:147], v[176:177], off
	global_load_dwordx4 v[148:151], v[178:179], off
	global_load_dwordx4 v[152:155], v[176:177], off offset:256
	global_load_dwordx4 v[156:159], v[178:179], off offset:256
	s_mov_b32 s98, 0x4000
	s_mov_b32 s99, 0
	v_lshl_add_u64 v[176:177], v[218:219], 0, s[98:99]
	v_lshl_add_u64 v[178:179], v[176:177], 0, s[0:1]
	global_load_dwordx4 v[160:163], v[176:177], off
	global_load_dwordx4 v[164:167], v[178:179], off
	global_load_dwordx4 v[168:171], v[176:177], off offset:256
	global_load_dwordx4 v[172:175], v[178:179], off offset:256
	s_waitcnt vmcnt(10)
	v_lshlrev_b32_e32 v184, 16, v132
	v_and_b32_e32 v185, 0xffff0000, v132
	v_lshlrev_b32_e32 v188, 16, v133
	v_and_b32_e32 v189, 0xffff0000, v133
	v_rcp_f32_e32 v184, v184
	v_rcp_f32_e32 v185, v185
	v_rcp_f32_e32 v188, v188
	v_rcp_f32_e32 v189, v189
	v_lshlrev_b32_e32 v186, 16, v128
	v_and_b32_e32 v187, 0xffff0000, v128
	v_lshlrev_b32_e32 v190, 16, v129
	v_and_b32_e32 v191, 0xffff0000, v129
	v_pk_mul_f32 v[184:185], v[184:185], v[186:187]
	v_pk_mul_f32 v[188:189], v[188:189], v[190:191]
	v_pk_mul_f32 v[124:125], v[124:125], v[184:185]
	v_pk_mul_f32 v[126:127], v[126:127], v[188:189]
	v_lshlrev_b32_e32 v184, 16, v134
	v_and_b32_e32 v185, 0xffff0000, v134
	v_lshlrev_b32_e32 v188, 16, v135
	v_and_b32_e32 v189, 0xffff0000, v135
	v_rcp_f32_e32 v184, v184
	v_rcp_f32_e32 v185, v185
	v_rcp_f32_e32 v188, v188
	v_rcp_f32_e32 v189, v189
	v_lshlrev_b32_e32 v186, 16, v130
	v_and_b32_e32 v187, 0xffff0000, v130
	v_lshlrev_b32_e32 v190, 16, v131
	v_and_b32_e32 v191, 0xffff0000, v131
	v_pk_mul_f32 v[184:185], v[184:185], v[186:187]
	v_pk_mul_f32 v[188:189], v[188:189], v[190:191]
	v_pk_mul_f32 v[120:121], v[120:121], v[184:185]
	v_pk_mul_f32 v[122:123], v[122:123], v[188:189]
	s_mov_b32 s98, 0x6000
	s_mov_b32 s99, 0
	v_lshl_add_u64 v[176:177], v[218:219], 0, s[98:99]
	v_lshl_add_u64 v[178:179], v[176:177], 0, s[0:1]
	global_load_dwordx4 v[128:131], v[176:177], off
	global_load_dwordx4 v[132:135], v[178:179], off
	s_waitcnt vmcnt(10)
	v_lshlrev_b32_e32 v184, 16, v140
	v_and_b32_e32 v185, 0xffff0000, v140
	v_lshlrev_b32_e32 v188, 16, v141
	v_and_b32_e32 v189, 0xffff0000, v141
	v_rcp_f32_e32 v184, v184
	v_rcp_f32_e32 v185, v185
	v_rcp_f32_e32 v188, v188
	v_rcp_f32_e32 v189, v189
	v_lshlrev_b32_e32 v186, 16, v136
	v_and_b32_e32 v187, 0xffff0000, v136
	v_lshlrev_b32_e32 v190, 16, v137
	v_and_b32_e32 v191, 0xffff0000, v137
	v_pk_mul_f32 v[184:185], v[184:185], v[186:187]
	v_pk_mul_f32 v[188:189], v[188:189], v[190:191]
	v_pk_mul_f32 v[92:93], v[92:93], v[184:185]
	v_pk_mul_f32 v[94:95], v[94:95], v[188:189]
	v_lshlrev_b32_e32 v184, 16, v142
	v_and_b32_e32 v185, 0xffff0000, v142
	v_lshlrev_b32_e32 v188, 16, v143
	v_and_b32_e32 v189, 0xffff0000, v143
	v_rcp_f32_e32 v184, v184
	v_rcp_f32_e32 v185, v185
	v_rcp_f32_e32 v188, v188
	v_rcp_f32_e32 v189, v189
	v_lshlrev_b32_e32 v186, 16, v138
	v_and_b32_e32 v187, 0xffff0000, v138
	v_lshlrev_b32_e32 v190, 16, v139
	v_and_b32_e32 v191, 0xffff0000, v139
	v_pk_mul_f32 v[184:185], v[184:185], v[186:187]
	v_pk_mul_f32 v[188:189], v[188:189], v[190:191]
	v_pk_mul_f32 v[88:89], v[88:89], v[184:185]
	v_pk_mul_f32 v[90:91], v[90:91], v[188:189]
	global_load_dwordx4 v[136:139], v[176:177], off offset:256
	global_load_dwordx4 v[140:143], v[178:179], off offset:256
	s_waitcnt vmcnt(10)
	v_lshlrev_b32_e32 v184, 16, v148
	v_and_b32_e32 v185, 0xffff0000, v148
	v_lshlrev_b32_e32 v188, 16, v149
	v_and_b32_e32 v189, 0xffff0000, v149
	v_rcp_f32_e32 v184, v184
	v_rcp_f32_e32 v185, v185
	v_rcp_f32_e32 v188, v188
	v_rcp_f32_e32 v189, v189
	v_lshlrev_b32_e32 v186, 16, v144
	v_and_b32_e32 v187, 0xffff0000, v144
	v_lshlrev_b32_e32 v190, 16, v145
	v_and_b32_e32 v191, 0xffff0000, v145
	v_pk_mul_f32 v[184:185], v[184:185], v[186:187]
	v_pk_mul_f32 v[188:189], v[188:189], v[190:191]
	v_pk_mul_f32 v[116:117], v[116:117], v[184:185]
	v_pk_mul_f32 v[118:119], v[118:119], v[188:189]
	v_lshlrev_b32_e32 v184, 16, v150
	v_and_b32_e32 v185, 0xffff0000, v150
	v_lshlrev_b32_e32 v188, 16, v151
	v_and_b32_e32 v189, 0xffff0000, v151
	v_rcp_f32_e32 v184, v184
	v_rcp_f32_e32 v185, v185
	v_rcp_f32_e32 v188, v188
	v_rcp_f32_e32 v189, v189
	v_lshlrev_b32_e32 v186, 16, v146
	v_and_b32_e32 v187, 0xffff0000, v146
	v_lshlrev_b32_e32 v190, 16, v147
	v_and_b32_e32 v191, 0xffff0000, v147
	v_pk_mul_f32 v[184:185], v[184:185], v[186:187]
	v_pk_mul_f32 v[188:189], v[188:189], v[190:191]
	v_pk_mul_f32 v[112:113], v[112:113], v[184:185]
	v_pk_mul_f32 v[114:115], v[114:115], v[188:189]
	s_mov_b32 s98, 0x10000
	s_mov_b32 s99, 0
	v_lshl_add_u64 v[176:177], v[218:219], 0, s[98:99]
	v_lshl_add_u64 v[178:179], v[176:177], 0, s[0:1]
	global_load_dwordx4 v[144:147], v[176:177], off
	global_load_dwordx4 v[148:151], v[178:179], off
	s_waitcnt vmcnt(10)
	v_lshlrev_b32_e32 v184, 16, v156
	v_and_b32_e32 v185, 0xffff0000, v156
	v_lshlrev_b32_e32 v188, 16, v157
	v_and_b32_e32 v189, 0xffff0000, v157
	v_rcp_f32_e32 v184, v184
	v_rcp_f32_e32 v185, v185
	v_rcp_f32_e32 v188, v188
	v_rcp_f32_e32 v189, v189
	v_lshlrev_b32_e32 v186, 16, v152
	v_and_b32_e32 v187, 0xffff0000, v152
	v_lshlrev_b32_e32 v190, 16, v153
	v_and_b32_e32 v191, 0xffff0000, v153
	v_pk_mul_f32 v[184:185], v[184:185], v[186:187]
	v_pk_mul_f32 v[188:189], v[188:189], v[190:191]
	v_pk_mul_f32 v[84:85], v[84:85], v[184:185]
	v_pk_mul_f32 v[86:87], v[86:87], v[188:189]
	v_lshlrev_b32_e32 v184, 16, v158
	v_and_b32_e32 v185, 0xffff0000, v158
	v_lshlrev_b32_e32 v188, 16, v159
	v_and_b32_e32 v189, 0xffff0000, v159
	v_rcp_f32_e32 v184, v184
	v_rcp_f32_e32 v185, v185
	v_rcp_f32_e32 v188, v188
	v_rcp_f32_e32 v189, v189
	v_lshlrev_b32_e32 v186, 16, v154
	v_and_b32_e32 v187, 0xffff0000, v154
	v_lshlrev_b32_e32 v190, 16, v155
	v_and_b32_e32 v191, 0xffff0000, v155
	v_pk_mul_f32 v[184:185], v[184:185], v[186:187]
	v_pk_mul_f32 v[188:189], v[188:189], v[190:191]
	v_pk_mul_f32 v[80:81], v[80:81], v[184:185]
	v_pk_mul_f32 v[82:83], v[82:83], v[188:189]
	global_load_dwordx4 v[152:155], v[176:177], off offset:256
	global_load_dwordx4 v[156:159], v[178:179], off offset:256
	s_waitcnt vmcnt(10)
	v_lshlrev_b32_e32 v184, 16, v164
	v_and_b32_e32 v185, 0xffff0000, v164
	v_lshlrev_b32_e32 v188, 16, v165
	v_and_b32_e32 v189, 0xffff0000, v165
	v_rcp_f32_e32 v184, v184
	v_rcp_f32_e32 v185, v185
	v_rcp_f32_e32 v188, v188
	v_rcp_f32_e32 v189, v189
	v_lshlrev_b32_e32 v186, 16, v160
	v_and_b32_e32 v187, 0xffff0000, v160
	v_lshlrev_b32_e32 v190, 16, v161
	v_and_b32_e32 v191, 0xffff0000, v161
	v_pk_mul_f32 v[184:185], v[184:185], v[186:187]
	v_pk_mul_f32 v[188:189], v[188:189], v[190:191]
	v_pk_mul_f32 v[108:109], v[108:109], v[184:185]
	v_pk_mul_f32 v[110:111], v[110:111], v[188:189]
	v_lshlrev_b32_e32 v184, 16, v166
	v_and_b32_e32 v185, 0xffff0000, v166
	v_lshlrev_b32_e32 v188, 16, v167
	v_and_b32_e32 v189, 0xffff0000, v167
	v_rcp_f32_e32 v184, v184
	v_rcp_f32_e32 v185, v185
	v_rcp_f32_e32 v188, v188
	v_rcp_f32_e32 v189, v189
	v_lshlrev_b32_e32 v186, 16, v162
	v_and_b32_e32 v187, 0xffff0000, v162
	v_lshlrev_b32_e32 v190, 16, v163
	v_and_b32_e32 v191, 0xffff0000, v163
	v_pk_mul_f32 v[184:185], v[184:185], v[186:187]
	v_pk_mul_f32 v[188:189], v[188:189], v[190:191]
	v_pk_mul_f32 v[104:105], v[104:105], v[184:185]
	v_pk_mul_f32 v[106:107], v[106:107], v[188:189]
	s_mov_b32 s98, 0x12000
	s_mov_b32 s99, 0
	v_lshl_add_u64 v[176:177], v[218:219], 0, s[98:99]
	v_lshl_add_u64 v[178:179], v[176:177], 0, s[0:1]
	global_load_dwordx4 v[160:163], v[176:177], off
	global_load_dwordx4 v[164:167], v[178:179], off
	s_waitcnt vmcnt(10)
	v_lshlrev_b32_e32 v184, 16, v172
	v_and_b32_e32 v185, 0xffff0000, v172
	v_lshlrev_b32_e32 v188, 16, v173
	v_and_b32_e32 v189, 0xffff0000, v173
	v_rcp_f32_e32 v184, v184
	v_rcp_f32_e32 v185, v185
	v_rcp_f32_e32 v188, v188
	v_rcp_f32_e32 v189, v189
	v_lshlrev_b32_e32 v186, 16, v168
	v_and_b32_e32 v187, 0xffff0000, v168
	v_lshlrev_b32_e32 v190, 16, v169
	v_and_b32_e32 v191, 0xffff0000, v169
	v_pk_mul_f32 v[184:185], v[184:185], v[186:187]
	v_pk_mul_f32 v[188:189], v[188:189], v[190:191]
	v_pk_mul_f32 v[76:77], v[76:77], v[184:185]
	v_pk_mul_f32 v[78:79], v[78:79], v[188:189]
	v_lshlrev_b32_e32 v184, 16, v174
	v_and_b32_e32 v185, 0xffff0000, v174
	v_lshlrev_b32_e32 v188, 16, v175
	v_and_b32_e32 v189, 0xffff0000, v175
	v_rcp_f32_e32 v184, v184
	v_rcp_f32_e32 v185, v185
	v_rcp_f32_e32 v188, v188
	v_rcp_f32_e32 v189, v189
	v_lshlrev_b32_e32 v186, 16, v170
	v_and_b32_e32 v187, 0xffff0000, v170
	v_lshlrev_b32_e32 v190, 16, v171
	v_and_b32_e32 v191, 0xffff0000, v171
	v_pk_mul_f32 v[184:185], v[184:185], v[186:187]
	v_pk_mul_f32 v[188:189], v[188:189], v[190:191]
	v_pk_mul_f32 v[72:73], v[72:73], v[184:185]
	v_pk_mul_f32 v[74:75], v[74:75], v[188:189]
	global_load_dwordx4 v[168:171], v[176:177], off offset:256
	global_load_dwordx4 v[172:175], v[178:179], off offset:256
	s_waitcnt vmcnt(10)
	v_lshlrev_b32_e32 v184, 16, v132
	v_and_b32_e32 v185, 0xffff0000, v132
	v_lshlrev_b32_e32 v188, 16, v133
	v_and_b32_e32 v189, 0xffff0000, v133
	v_rcp_f32_e32 v184, v184
	v_rcp_f32_e32 v185, v185
	v_rcp_f32_e32 v188, v188
	v_rcp_f32_e32 v189, v189
	v_lshlrev_b32_e32 v186, 16, v128
	v_and_b32_e32 v187, 0xffff0000, v128
	v_lshlrev_b32_e32 v190, 16, v129
	v_and_b32_e32 v191, 0xffff0000, v129
	v_pk_mul_f32 v[184:185], v[184:185], v[186:187]
	v_pk_mul_f32 v[188:189], v[188:189], v[190:191]
	v_pk_mul_f32 v[100:101], v[100:101], v[184:185]
	v_pk_mul_f32 v[102:103], v[102:103], v[188:189]
	v_lshlrev_b32_e32 v184, 16, v134
	v_and_b32_e32 v185, 0xffff0000, v134
	v_lshlrev_b32_e32 v188, 16, v135
	v_and_b32_e32 v189, 0xffff0000, v135
	v_rcp_f32_e32 v184, v184
	v_rcp_f32_e32 v185, v185
	v_rcp_f32_e32 v188, v188
	v_rcp_f32_e32 v189, v189
	v_lshlrev_b32_e32 v186, 16, v130
	v_and_b32_e32 v187, 0xffff0000, v130
	v_lshlrev_b32_e32 v190, 16, v131
	v_and_b32_e32 v191, 0xffff0000, v131
	v_pk_mul_f32 v[184:185], v[184:185], v[186:187]
	v_pk_mul_f32 v[188:189], v[188:189], v[190:191]
	v_pk_mul_f32 v[96:97], v[96:97], v[184:185]
	v_pk_mul_f32 v[98:99], v[98:99], v[188:189]
	s_mov_b32 s98, 0x14000
	s_mov_b32 s99, 0
	v_lshl_add_u64 v[176:177], v[218:219], 0, s[98:99]
	v_lshl_add_u64 v[178:179], v[176:177], 0, s[0:1]
	global_load_dwordx4 v[128:131], v[176:177], off
	global_load_dwordx4 v[132:135], v[178:179], off
	s_waitcnt vmcnt(10)
	v_lshlrev_b32_e32 v184, 16, v140
	v_and_b32_e32 v185, 0xffff0000, v140
	v_lshlrev_b32_e32 v188, 16, v141
	v_and_b32_e32 v189, 0xffff0000, v141
	v_rcp_f32_e32 v184, v184
	v_rcp_f32_e32 v185, v185
	v_rcp_f32_e32 v188, v188
	v_rcp_f32_e32 v189, v189
	v_lshlrev_b32_e32 v186, 16, v136
	v_and_b32_e32 v187, 0xffff0000, v136
	v_lshlrev_b32_e32 v190, 16, v137
	v_and_b32_e32 v191, 0xffff0000, v137
	v_pk_mul_f32 v[184:185], v[184:185], v[186:187]
	v_pk_mul_f32 v[188:189], v[188:189], v[190:191]
	v_pk_mul_f32 v[68:69], v[68:69], v[184:185]
	v_pk_mul_f32 v[70:71], v[70:71], v[188:189]
	v_lshlrev_b32_e32 v184, 16, v142
	v_and_b32_e32 v185, 0xffff0000, v142
	v_lshlrev_b32_e32 v188, 16, v143
	v_and_b32_e32 v189, 0xffff0000, v143
	v_rcp_f32_e32 v184, v184
	v_rcp_f32_e32 v185, v185
	v_rcp_f32_e32 v188, v188
	v_rcp_f32_e32 v189, v189
	v_lshlrev_b32_e32 v186, 16, v138
	v_and_b32_e32 v187, 0xffff0000, v138
	v_lshlrev_b32_e32 v190, 16, v139
	v_and_b32_e32 v191, 0xffff0000, v139
	v_pk_mul_f32 v[184:185], v[184:185], v[186:187]
	v_pk_mul_f32 v[188:189], v[188:189], v[190:191]
	v_pk_mul_f32 v[64:65], v[64:65], v[184:185]
	v_pk_mul_f32 v[66:67], v[66:67], v[188:189]
	global_load_dwordx4 v[136:139], v[176:177], off offset:256
	global_load_dwordx4 v[140:143], v[178:179], off offset:256
	s_waitcnt vmcnt(10)
	v_lshlrev_b32_e32 v184, 16, v148
	v_and_b32_e32 v185, 0xffff0000, v148
	v_lshlrev_b32_e32 v188, 16, v149
	v_and_b32_e32 v189, 0xffff0000, v149
	v_rcp_f32_e32 v184, v184
	v_rcp_f32_e32 v185, v185
	v_rcp_f32_e32 v188, v188
	v_rcp_f32_e32 v189, v189
	v_lshlrev_b32_e32 v186, 16, v144
	v_and_b32_e32 v187, 0xffff0000, v144
	v_lshlrev_b32_e32 v190, 16, v145
	v_and_b32_e32 v191, 0xffff0000, v145
	v_pk_mul_f32 v[184:185], v[184:185], v[186:187]
	v_pk_mul_f32 v[188:189], v[188:189], v[190:191]
	v_pk_mul_f32 v[60:61], v[60:61], v[184:185]
	v_pk_mul_f32 v[62:63], v[62:63], v[188:189]
	v_lshlrev_b32_e32 v184, 16, v150
	v_and_b32_e32 v185, 0xffff0000, v150
	v_lshlrev_b32_e32 v188, 16, v151
	v_and_b32_e32 v189, 0xffff0000, v151
	v_rcp_f32_e32 v184, v184
	v_rcp_f32_e32 v185, v185
	v_rcp_f32_e32 v188, v188
	v_rcp_f32_e32 v189, v189
	v_lshlrev_b32_e32 v186, 16, v146
	v_and_b32_e32 v187, 0xffff0000, v146
	v_lshlrev_b32_e32 v190, 16, v147
	v_and_b32_e32 v191, 0xffff0000, v147
	v_pk_mul_f32 v[184:185], v[184:185], v[186:187]
	v_pk_mul_f32 v[188:189], v[188:189], v[190:191]
	v_pk_mul_f32 v[56:57], v[56:57], v[184:185]
	v_pk_mul_f32 v[58:59], v[58:59], v[188:189]
	s_mov_b32 s98, 0x16000
	s_mov_b32 s99, 0
	v_lshl_add_u64 v[176:177], v[218:219], 0, s[98:99]
	v_lshl_add_u64 v[178:179], v[176:177], 0, s[0:1]
	global_load_dwordx4 v[144:147], v[176:177], off
	global_load_dwordx4 v[148:151], v[178:179], off
	s_waitcnt vmcnt(10)
	v_lshlrev_b32_e32 v184, 16, v156
	v_and_b32_e32 v185, 0xffff0000, v156
	v_lshlrev_b32_e32 v188, 16, v157
	v_and_b32_e32 v189, 0xffff0000, v157
	v_rcp_f32_e32 v184, v184
	v_rcp_f32_e32 v185, v185
	v_rcp_f32_e32 v188, v188
	v_rcp_f32_e32 v189, v189
	v_lshlrev_b32_e32 v186, 16, v152
	v_and_b32_e32 v187, 0xffff0000, v152
	v_lshlrev_b32_e32 v190, 16, v153
	v_and_b32_e32 v191, 0xffff0000, v153
	v_pk_mul_f32 v[184:185], v[184:185], v[186:187]
	v_pk_mul_f32 v[188:189], v[188:189], v[190:191]
	v_pk_mul_f32 v[28:29], v[28:29], v[184:185]
	v_pk_mul_f32 v[30:31], v[30:31], v[188:189]
	v_lshlrev_b32_e32 v184, 16, v158
	v_and_b32_e32 v185, 0xffff0000, v158
	v_lshlrev_b32_e32 v188, 16, v159
	v_and_b32_e32 v189, 0xffff0000, v159
	v_rcp_f32_e32 v184, v184
	v_rcp_f32_e32 v185, v185
	v_rcp_f32_e32 v188, v188
	v_rcp_f32_e32 v189, v189
	v_lshlrev_b32_e32 v186, 16, v154
	v_and_b32_e32 v187, 0xffff0000, v154
	v_lshlrev_b32_e32 v190, 16, v155
	v_and_b32_e32 v191, 0xffff0000, v155
	v_pk_mul_f32 v[184:185], v[184:185], v[186:187]
	v_pk_mul_f32 v[188:189], v[188:189], v[190:191]
	v_pk_mul_f32 v[24:25], v[24:25], v[184:185]
	v_pk_mul_f32 v[26:27], v[26:27], v[188:189]
	global_load_dwordx4 v[152:155], v[176:177], off offset:256
	global_load_dwordx4 v[156:159], v[178:179], off offset:256
	s_waitcnt vmcnt(10)
	v_lshlrev_b32_e32 v184, 16, v164
	v_and_b32_e32 v185, 0xffff0000, v164
	v_lshlrev_b32_e32 v188, 16, v165
	v_and_b32_e32 v189, 0xffff0000, v165
	v_rcp_f32_e32 v184, v184
	v_rcp_f32_e32 v185, v185
	v_rcp_f32_e32 v188, v188
	v_rcp_f32_e32 v189, v189
	v_lshlrev_b32_e32 v186, 16, v160
	v_and_b32_e32 v187, 0xffff0000, v160
	v_lshlrev_b32_e32 v190, 16, v161
	v_and_b32_e32 v191, 0xffff0000, v161
	v_pk_mul_f32 v[184:185], v[184:185], v[186:187]
	v_pk_mul_f32 v[188:189], v[188:189], v[190:191]
	v_pk_mul_f32 v[52:53], v[52:53], v[184:185]
	v_pk_mul_f32 v[54:55], v[54:55], v[188:189]
	v_lshlrev_b32_e32 v184, 16, v166
	v_and_b32_e32 v185, 0xffff0000, v166
	v_lshlrev_b32_e32 v188, 16, v167
	v_and_b32_e32 v189, 0xffff0000, v167
	v_rcp_f32_e32 v184, v184
	v_rcp_f32_e32 v185, v185
	v_rcp_f32_e32 v188, v188
	v_rcp_f32_e32 v189, v189
	v_lshlrev_b32_e32 v186, 16, v162
	v_and_b32_e32 v187, 0xffff0000, v162
	v_lshlrev_b32_e32 v190, 16, v163
	v_and_b32_e32 v191, 0xffff0000, v163
	v_pk_mul_f32 v[184:185], v[184:185], v[186:187]
	v_pk_mul_f32 v[188:189], v[188:189], v[190:191]
	v_pk_mul_f32 v[48:49], v[48:49], v[184:185]
	v_pk_mul_f32 v[50:51], v[50:51], v[188:189]
	s_waitcnt vmcnt(8)
	v_lshlrev_b32_e32 v184, 16, v172
	v_and_b32_e32 v185, 0xffff0000, v172
	v_lshlrev_b32_e32 v188, 16, v173
	v_and_b32_e32 v189, 0xffff0000, v173
	v_rcp_f32_e32 v184, v184
	v_rcp_f32_e32 v185, v185
	v_rcp_f32_e32 v188, v188
	v_rcp_f32_e32 v189, v189
	v_lshlrev_b32_e32 v186, 16, v168
	v_and_b32_e32 v187, 0xffff0000, v168
	v_lshlrev_b32_e32 v190, 16, v169
	v_and_b32_e32 v191, 0xffff0000, v169
	v_pk_mul_f32 v[184:185], v[184:185], v[186:187]
	v_pk_mul_f32 v[188:189], v[188:189], v[190:191]
	v_pk_mul_f32 v[20:21], v[20:21], v[184:185]
	v_pk_mul_f32 v[22:23], v[22:23], v[188:189]
	v_lshlrev_b32_e32 v184, 16, v174
	v_and_b32_e32 v185, 0xffff0000, v174
	v_lshlrev_b32_e32 v188, 16, v175
	v_and_b32_e32 v189, 0xffff0000, v175
	v_rcp_f32_e32 v184, v184
	v_rcp_f32_e32 v185, v185
	v_rcp_f32_e32 v188, v188
	v_rcp_f32_e32 v189, v189
	v_lshlrev_b32_e32 v186, 16, v170
	v_and_b32_e32 v187, 0xffff0000, v170
	v_lshlrev_b32_e32 v190, 16, v171
	v_and_b32_e32 v191, 0xffff0000, v171
	v_pk_mul_f32 v[184:185], v[184:185], v[186:187]
	v_pk_mul_f32 v[188:189], v[188:189], v[190:191]
	v_pk_mul_f32 v[16:17], v[16:17], v[184:185]
	v_pk_mul_f32 v[18:19], v[18:19], v[188:189]
	s_waitcnt vmcnt(6)
	v_lshlrev_b32_e32 v184, 16, v132
	v_and_b32_e32 v185, 0xffff0000, v132
	v_lshlrev_b32_e32 v188, 16, v133
	v_and_b32_e32 v189, 0xffff0000, v133
	v_rcp_f32_e32 v184, v184
	v_rcp_f32_e32 v185, v185
	v_rcp_f32_e32 v188, v188
	v_rcp_f32_e32 v189, v189
	v_lshlrev_b32_e32 v186, 16, v128
	v_and_b32_e32 v187, 0xffff0000, v128
	v_lshlrev_b32_e32 v190, 16, v129
	v_and_b32_e32 v191, 0xffff0000, v129
	v_pk_mul_f32 v[184:185], v[184:185], v[186:187]
	v_pk_mul_f32 v[188:189], v[188:189], v[190:191]
	v_pk_mul_f32 v[44:45], v[44:45], v[184:185]
	v_pk_mul_f32 v[46:47], v[46:47], v[188:189]
	v_lshlrev_b32_e32 v184, 16, v134
	v_and_b32_e32 v185, 0xffff0000, v134
	v_lshlrev_b32_e32 v188, 16, v135
	v_and_b32_e32 v189, 0xffff0000, v135
	v_rcp_f32_e32 v184, v184
	v_rcp_f32_e32 v185, v185
	v_rcp_f32_e32 v188, v188
	v_rcp_f32_e32 v189, v189
	v_lshlrev_b32_e32 v186, 16, v130
	v_and_b32_e32 v187, 0xffff0000, v130
	v_lshlrev_b32_e32 v190, 16, v131
	v_and_b32_e32 v191, 0xffff0000, v131
	v_pk_mul_f32 v[184:185], v[184:185], v[186:187]
	v_pk_mul_f32 v[188:189], v[188:189], v[190:191]
	v_pk_mul_f32 v[40:41], v[40:41], v[184:185]
	v_pk_mul_f32 v[42:43], v[42:43], v[188:189]
	s_waitcnt vmcnt(4)
	v_lshlrev_b32_e32 v184, 16, v140
	v_and_b32_e32 v185, 0xffff0000, v140
	v_lshlrev_b32_e32 v188, 16, v141
	v_and_b32_e32 v189, 0xffff0000, v141
	v_rcp_f32_e32 v184, v184
	v_rcp_f32_e32 v185, v185
	v_rcp_f32_e32 v188, v188
	v_rcp_f32_e32 v189, v189
	v_lshlrev_b32_e32 v186, 16, v136
	v_and_b32_e32 v187, 0xffff0000, v136
	v_lshlrev_b32_e32 v190, 16, v137
	v_and_b32_e32 v191, 0xffff0000, v137
	v_pk_mul_f32 v[184:185], v[184:185], v[186:187]
	v_pk_mul_f32 v[188:189], v[188:189], v[190:191]
	v_pk_mul_f32 v[12:13], v[12:13], v[184:185]
	v_pk_mul_f32 v[14:15], v[14:15], v[188:189]
	v_lshlrev_b32_e32 v184, 16, v142
	v_and_b32_e32 v185, 0xffff0000, v142
	v_lshlrev_b32_e32 v188, 16, v143
	v_and_b32_e32 v189, 0xffff0000, v143
	v_rcp_f32_e32 v184, v184
	v_rcp_f32_e32 v185, v185
	v_rcp_f32_e32 v188, v188
	v_rcp_f32_e32 v189, v189
	v_lshlrev_b32_e32 v186, 16, v138
	v_and_b32_e32 v187, 0xffff0000, v138
	v_lshlrev_b32_e32 v190, 16, v139
	v_and_b32_e32 v191, 0xffff0000, v139
	v_pk_mul_f32 v[184:185], v[184:185], v[186:187]
	v_pk_mul_f32 v[188:189], v[188:189], v[190:191]
	v_pk_mul_f32 v[8:9], v[8:9], v[184:185]
	v_pk_mul_f32 v[10:11], v[10:11], v[188:189]
	s_waitcnt vmcnt(2)
	v_lshlrev_b32_e32 v184, 16, v148
	v_and_b32_e32 v185, 0xffff0000, v148
	v_lshlrev_b32_e32 v188, 16, v149
	v_and_b32_e32 v189, 0xffff0000, v149
	v_rcp_f32_e32 v184, v184
	v_rcp_f32_e32 v185, v185
	v_rcp_f32_e32 v188, v188
	v_rcp_f32_e32 v189, v189
	v_lshlrev_b32_e32 v186, 16, v144
	v_and_b32_e32 v187, 0xffff0000, v144
	v_lshlrev_b32_e32 v190, 16, v145
	v_and_b32_e32 v191, 0xffff0000, v145
	v_pk_mul_f32 v[184:185], v[184:185], v[186:187]
	v_pk_mul_f32 v[188:189], v[188:189], v[190:191]
	v_pk_mul_f32 v[36:37], v[36:37], v[184:185]
	v_pk_mul_f32 v[38:39], v[38:39], v[188:189]
	v_lshlrev_b32_e32 v184, 16, v150
	v_and_b32_e32 v185, 0xffff0000, v150
	v_lshlrev_b32_e32 v188, 16, v151
	v_and_b32_e32 v189, 0xffff0000, v151
	v_rcp_f32_e32 v184, v184
	v_rcp_f32_e32 v185, v185
	v_rcp_f32_e32 v188, v188
	v_rcp_f32_e32 v189, v189
	v_lshlrev_b32_e32 v186, 16, v146
	v_and_b32_e32 v187, 0xffff0000, v146
	v_lshlrev_b32_e32 v190, 16, v147
	v_and_b32_e32 v191, 0xffff0000, v147
	v_pk_mul_f32 v[184:185], v[184:185], v[186:187]
	v_pk_mul_f32 v[188:189], v[188:189], v[190:191]
	v_pk_mul_f32 v[32:33], v[32:33], v[184:185]
	v_pk_mul_f32 v[34:35], v[34:35], v[188:189]
	s_waitcnt vmcnt(0)
	v_lshlrev_b32_e32 v184, 16, v156
	v_and_b32_e32 v185, 0xffff0000, v156
	v_lshlrev_b32_e32 v188, 16, v157
	v_and_b32_e32 v189, 0xffff0000, v157
	v_rcp_f32_e32 v184, v184
	v_rcp_f32_e32 v185, v185
	v_rcp_f32_e32 v188, v188
	v_rcp_f32_e32 v189, v189
	v_lshlrev_b32_e32 v186, 16, v152
	v_and_b32_e32 v187, 0xffff0000, v152
	v_lshlrev_b32_e32 v190, 16, v153
	v_and_b32_e32 v191, 0xffff0000, v153
	v_pk_mul_f32 v[184:185], v[184:185], v[186:187]
	v_pk_mul_f32 v[188:189], v[188:189], v[190:191]
	v_pk_mul_f32 v[4:5], v[4:5], v[184:185]
	v_pk_mul_f32 v[6:7], v[6:7], v[188:189]
	v_lshlrev_b32_e32 v184, 16, v158
	v_and_b32_e32 v185, 0xffff0000, v158
	v_lshlrev_b32_e32 v188, 16, v159
	v_and_b32_e32 v189, 0xffff0000, v159
	v_rcp_f32_e32 v184, v184
	v_rcp_f32_e32 v185, v185
	v_rcp_f32_e32 v188, v188
	v_rcp_f32_e32 v189, v189
	v_lshlrev_b32_e32 v186, 16, v154
	v_and_b32_e32 v187, 0xffff0000, v154
	v_lshlrev_b32_e32 v190, 16, v155
	v_and_b32_e32 v191, 0xffff0000, v155
	v_pk_mul_f32 v[184:185], v[184:185], v[186:187]
	v_pk_mul_f32 v[188:189], v[188:189], v[190:191]
	v_pk_mul_f32 v[0:1], v[0:1], v[184:185]
	v_pk_mul_f32 v[2:3], v[2:3], v[188:189]
	s_mov_b64 s[2:3], -1
	s_branch .Lmg_done
.Lmg_final:
	s_mov_b32 s98, 0x0
	s_mov_b32 s99, 0
	v_lshl_add_u64 v[180:181], v[218:219], 0, s[98:99]
	global_load_dwordx4 v[128:131], v[180:181], off
	global_load_dwordx4 v[132:135], v[180:181], off offset:256
	s_mov_b32 s98, 0x2000
	s_mov_b32 s99, 0
	v_lshl_add_u64 v[180:181], v[218:219], 0, s[98:99]
	global_load_dwordx4 v[136:139], v[180:181], off
	global_load_dwordx4 v[140:143], v[180:181], off offset:256
	s_mov_b32 s98, 0x4000
	s_mov_b32 s99, 0
	v_lshl_add_u64 v[180:181], v[218:219], 0, s[98:99]
	global_load_dwordx4 v[144:147], v[180:181], off
	global_load_dwordx4 v[148:151], v[180:181], off offset:256
	s_mov_b32 s98, 0x6000
	s_mov_b32 s99, 0
	v_lshl_add_u64 v[180:181], v[218:219], 0, s[98:99]
	global_load_dwordx4 v[152:155], v[180:181], off
	global_load_dwordx4 v[156:159], v[180:181], off offset:256
	s_mov_b32 s98, 0x10000
	s_mov_b32 s99, 0
	v_lshl_add_u64 v[180:181], v[218:219], 0, s[98:99]
	global_load_dwordx4 v[160:163], v[180:181], off
	global_load_dwordx4 v[164:167], v[180:181], off offset:256
	s_mov_b32 s98, 0x12000
	s_mov_b32 s99, 0
	v_lshl_add_u64 v[180:181], v[218:219], 0, s[98:99]
	global_load_dwordx4 v[168:171], v[180:181], off
	global_load_dwordx4 v[172:175], v[180:181], off offset:256
	s_waitcnt vmcnt(11)
	v_lshlrev_b32_e32 v184, 16, v128
	v_and_b32_e32 v185, 0xffff0000, v128
	v_lshlrev_b32_e32 v186, 16, v129
	v_and_b32_e32 v187, 0xffff0000, v129
	v_pk_mul_f32 v[124:125], v[124:125], v[184:185]
	v_pk_mul_f32 v[126:127], v[126:127], v[186:187]
	v_lshlrev_b32_e32 v184, 16, v130
	v_and_b32_e32 v185, 0xffff0000, v130
	v_lshlrev_b32_e32 v186, 16, v131
	v_and_b32_e32 v187, 0xffff0000, v131
	v_pk_mul_f32 v[120:121], v[120:121], v[184:185]
	v_pk_mul_f32 v[122:123], v[122:123], v[186:187]
	v_cvt_pk_bf16_f32 v176, v124, v125
	v_cvt_pk_bf16_f32 v177, v126, v127
	v_cvt_pk_bf16_f32 v178, v120, v121
	v_cvt_pk_bf16_f32 v179, v122, v123
	s_mov_b32 s98, 0x0
	s_mov_b32 s99, 0
	v_lshl_add_u64 v[182:183], v[216:217], 0, s[98:99]
	global_store_dwordx4 v[182:183], v[176:179], off
	s_mov_b32 s98, 0x14000
	s_mov_b32 s99, 0
	v_lshl_add_u64 v[180:181], v[218:219], 0, s[98:99]
	global_load_dwordx4 v[128:131], v[180:181], off
	s_waitcnt vmcnt(12)
	v_lshlrev_b32_e32 v184, 16, v132
	v_and_b32_e32 v185, 0xffff0000, v132
	v_lshlrev_b32_e32 v186, 16, v133
	v_and_b32_e32 v187, 0xffff0000, v133
	v_pk_mul_f32 v[92:93], v[92:93], v[184:185]
	v_pk_mul_f32 v[94:95], v[94:95], v[186:187]
	v_lshlrev_b32_e32 v184, 16, v134
	v_and_b32_e32 v185, 0xffff0000, v134
	v_lshlrev_b32_e32 v186, 16, v135
	v_and_b32_e32 v187, 0xffff0000, v135
	v_pk_mul_f32 v[88:89], v[88:89], v[184:185]
	v_pk_mul_f32 v[90:91], v[90:91], v[186:187]
	v_cvt_pk_bf16_f32 v188, v92, v93
	v_cvt_pk_bf16_f32 v189, v94, v95
	v_cvt_pk_bf16_f32 v190, v88, v89
	v_cvt_pk_bf16_f32 v191, v90, v91
	global_store_dwordx4 v[182:183], v[188:191], off offset:256
	global_load_dwordx4 v[132:135], v[180:181], off offset:256
	s_waitcnt vmcnt(13)
	v_lshlrev_b32_e32 v184, 16, v136
	v_and_b32_e32 v185, 0xffff0000, v136
	v_lshlrev_b32_e32 v186, 16, v137
	v_and_b32_e32 v187, 0xffff0000, v137
	v_pk_mul_f32 v[116:117], v[116:117], v[184:185]
	v_pk_mul_f32 v[118:119], v[118:119], v[186:187]
	v_lshlrev_b32_e32 v184, 16, v138
	v_and_b32_e32 v185, 0xffff0000, v138
	v_lshlrev_b32_e32 v186, 16, v139
	v_and_b32_e32 v187, 0xffff0000, v139
	v_pk_mul_f32 v[112:113], v[112:113], v[184:185]
	v_pk_mul_f32 v[114:115], v[114:115], v[186:187]
	v_cvt_pk_bf16_f32 v176, v116, v117
	v_cvt_pk_bf16_f32 v177, v118, v119
	v_cvt_pk_bf16_f32 v178, v112, v113
	v_cvt_pk_bf16_f32 v179, v114, v115
	s_mov_b32 s98, 0x8000
	s_mov_b32 s99, 0
	v_lshl_add_u64 v[182:183], v[216:217], 0, s[98:99]
	global_store_dwordx4 v[182:183], v[176:179], off
	s_mov_b32 s98, 0x16000
	s_mov_b32 s99, 0
	v_lshl_add_u64 v[180:181], v[218:219], 0, s[98:99]
	global_load_dwordx4 v[136:139], v[180:181], off
	s_waitcnt vmcnt(14)
	v_lshlrev_b32_e32 v184, 16, v140
	v_and_b32_e32 v185, 0xffff0000, v140
	v_lshlrev_b32_e32 v186, 16, v141
	v_and_b32_e32 v187, 0xffff0000, v141
	v_pk_mul_f32 v[84:85], v[84:85], v[184:185]
	v_pk_mul_f32 v[86:87], v[86:87], v[186:187]
	v_lshlrev_b32_e32 v184, 16, v142
	v_and_b32_e32 v185, 0xffff0000, v142
	v_lshlrev_b32_e32 v186, 16, v143
	v_and_b32_e32 v187, 0xffff0000, v143
	v_pk_mul_f32 v[80:81], v[80:81], v[184:185]
	v_pk_mul_f32 v[82:83], v[82:83], v[186:187]
	v_cvt_pk_bf16_f32 v188, v84, v85
	v_cvt_pk_bf16_f32 v189, v86, v87
	v_cvt_pk_bf16_f32 v190, v80, v81
	v_cvt_pk_bf16_f32 v191, v82, v83
	global_store_dwordx4 v[182:183], v[188:191], off offset:256
	global_load_dwordx4 v[140:143], v[180:181], off offset:256
	s_waitcnt vmcnt(15)
	v_lshlrev_b32_e32 v184, 16, v144
	v_and_b32_e32 v185, 0xffff0000, v144
	v_lshlrev_b32_e32 v186, 16, v145
	v_and_b32_e32 v187, 0xffff0000, v145
	v_pk_mul_f32 v[108:109], v[108:109], v[184:185]
	v_pk_mul_f32 v[110:111], v[110:111], v[186:187]
	v_lshlrev_b32_e32 v184, 16, v146
	v_and_b32_e32 v185, 0xffff0000, v146
	v_lshlrev_b32_e32 v186, 16, v147
	v_and_b32_e32 v187, 0xffff0000, v147
	v_pk_mul_f32 v[104:105], v[104:105], v[184:185]
	v_pk_mul_f32 v[106:107], v[106:107], v[186:187]
	v_cvt_pk_bf16_f32 v176, v108, v109
	v_cvt_pk_bf16_f32 v177, v110, v111
	v_cvt_pk_bf16_f32 v178, v104, v105
	v_cvt_pk_bf16_f32 v179, v106, v107
	s_mov_b32 s98, 0x10000
	s_mov_b32 s99, 0
	v_lshl_add_u64 v[182:183], v[216:217], 0, s[98:99]
	global_store_dwordx4 v[182:183], v[176:179], off
	s_waitcnt vmcnt(15)
	v_lshlrev_b32_e32 v184, 16, v148
	v_and_b32_e32 v185, 0xffff0000, v148
	v_lshlrev_b32_e32 v186, 16, v149
	v_and_b32_e32 v187, 0xffff0000, v149
	v_pk_mul_f32 v[76:77], v[76:77], v[184:185]
	v_pk_mul_f32 v[78:79], v[78:79], v[186:187]
	v_lshlrev_b32_e32 v184, 16, v150
	v_and_b32_e32 v185, 0xffff0000, v150
	v_lshlrev_b32_e32 v186, 16, v151
	v_and_b32_e32 v187, 0xffff0000, v151
	v_pk_mul_f32 v[72:73], v[72:73], v[184:185]
	v_pk_mul_f32 v[74:75], v[74:75], v[186:187]
	v_cvt_pk_bf16_f32 v188, v76, v77
	v_cvt_pk_bf16_f32 v189, v78, v79
	v_cvt_pk_bf16_f32 v190, v72, v73
	v_cvt_pk_bf16_f32 v191, v74, v75
	global_store_dwordx4 v[182:183], v[188:191], off offset:256
	s_waitcnt vmcnt(15)
	v_lshlrev_b32_e32 v184, 16, v152
	v_and_b32_e32 v185, 0xffff0000, v152
	v_lshlrev_b32_e32 v186, 16, v153
	v_and_b32_e32 v187, 0xffff0000, v153
	v_pk_mul_f32 v[100:101], v[100:101], v[184:185]
	v_pk_mul_f32 v[102:103], v[102:103], v[186:187]
	v_lshlrev_b32_e32 v184, 16, v154
	v_and_b32_e32 v185, 0xffff0000, v154
	v_lshlrev_b32_e32 v186, 16, v155
	v_and_b32_e32 v187, 0xffff0000, v155
	v_pk_mul_f32 v[96:97], v[96:97], v[184:185]
	v_pk_mul_f32 v[98:99], v[98:99], v[186:187]
	v_cvt_pk_bf16_f32 v176, v100, v101
	v_cvt_pk_bf16_f32 v177, v102, v103
	v_cvt_pk_bf16_f32 v178, v96, v97
	v_cvt_pk_bf16_f32 v179, v98, v99
	s_mov_b32 s98, 0x18000
	s_mov_b32 s99, 0
	v_lshl_add_u64 v[182:183], v[216:217], 0, s[98:99]
	global_store_dwordx4 v[182:183], v[176:179], off
	s_waitcnt vmcnt(15)
	v_lshlrev_b32_e32 v184, 16, v156
	v_and_b32_e32 v185, 0xffff0000, v156
	v_lshlrev_b32_e32 v186, 16, v157
	v_and_b32_e32 v187, 0xffff0000, v157
	v_pk_mul_f32 v[68:69], v[68:69], v[184:185]
	v_pk_mul_f32 v[70:71], v[70:71], v[186:187]
	v_lshlrev_b32_e32 v184, 16, v158
	v_and_b32_e32 v185, 0xffff0000, v158
	v_lshlrev_b32_e32 v186, 16, v159
	v_and_b32_e32 v187, 0xffff0000, v159
	v_pk_mul_f32 v[64:65], v[64:65], v[184:185]
	v_pk_mul_f32 v[66:67], v[66:67], v[186:187]
	v_cvt_pk_bf16_f32 v188, v68, v69
	v_cvt_pk_bf16_f32 v189, v70, v71
	v_cvt_pk_bf16_f32 v190, v64, v65
	v_cvt_pk_bf16_f32 v191, v66, v67
	global_store_dwordx4 v[182:183], v[188:191], off offset:256
	s_waitcnt vmcnt(15)
	v_lshlrev_b32_e32 v184, 16, v160
	v_and_b32_e32 v185, 0xffff0000, v160
	v_lshlrev_b32_e32 v186, 16, v161
	v_and_b32_e32 v187, 0xffff0000, v161
	v_pk_mul_f32 v[60:61], v[60:61], v[184:185]
	v_pk_mul_f32 v[62:63], v[62:63], v[186:187]
	v_lshlrev_b32_e32 v184, 16, v162
	v_and_b32_e32 v185, 0xffff0000, v162
	v_lshlrev_b32_e32 v186, 16, v163
	v_and_b32_e32 v187, 0xffff0000, v163
	v_pk_mul_f32 v[56:57], v[56:57], v[184:185]
	v_pk_mul_f32 v[58:59], v[58:59], v[186:187]
	v_cvt_pk_bf16_f32 v176, v60, v61
	v_cvt_pk_bf16_f32 v177, v62, v63
	v_cvt_pk_bf16_f32 v178, v56, v57
	v_cvt_pk_bf16_f32 v179, v58, v59
	s_mov_b32 s98, 0x40000
	s_mov_b32 s99, 0
	v_lshl_add_u64 v[182:183], v[216:217], 0, s[98:99]
	global_store_dwordx4 v[182:183], v[176:179], off
	s_waitcnt vmcnt(15)
	v_lshlrev_b32_e32 v184, 16, v164
	v_and_b32_e32 v185, 0xffff0000, v164
	v_lshlrev_b32_e32 v186, 16, v165
	v_and_b32_e32 v187, 0xffff0000, v165
	v_pk_mul_f32 v[28:29], v[28:29], v[184:185]
	v_pk_mul_f32 v[30:31], v[30:31], v[186:187]
	v_lshlrev_b32_e32 v184, 16, v166
	v_and_b32_e32 v185, 0xffff0000, v166
	v_lshlrev_b32_e32 v186, 16, v167
	v_and_b32_e32 v187, 0xffff0000, v167
	v_pk_mul_f32 v[24:25], v[24:25], v[184:185]
	v_pk_mul_f32 v[26:27], v[26:27], v[186:187]
	v_cvt_pk_bf16_f32 v188, v28, v29
	v_cvt_pk_bf16_f32 v189, v30, v31
	v_cvt_pk_bf16_f32 v190, v24, v25
	v_cvt_pk_bf16_f32 v191, v26, v27
	global_store_dwordx4 v[182:183], v[188:191], off offset:256
	s_waitcnt vmcnt(15)
	v_lshlrev_b32_e32 v184, 16, v168
	v_and_b32_e32 v185, 0xffff0000, v168
	v_lshlrev_b32_e32 v186, 16, v169
	v_and_b32_e32 v187, 0xffff0000, v169
	v_pk_mul_f32 v[52:53], v[52:53], v[184:185]
	v_pk_mul_f32 v[54:55], v[54:55], v[186:187]
	v_lshlrev_b32_e32 v184, 16, v170
	v_and_b32_e32 v185, 0xffff0000, v170
	v_lshlrev_b32_e32 v186, 16, v171
	v_and_b32_e32 v187, 0xffff0000, v171
	v_pk_mul_f32 v[48:49], v[48:49], v[184:185]
	v_pk_mul_f32 v[50:51], v[50:51], v[186:187]
	v_cvt_pk_bf16_f32 v176, v52, v53
	v_cvt_pk_bf16_f32 v177, v54, v55
	v_cvt_pk_bf16_f32 v178, v48, v49
	v_cvt_pk_bf16_f32 v179, v50, v51
	s_mov_b32 s98, 0x48000
	s_mov_b32 s99, 0
	v_lshl_add_u64 v[182:183], v[216:217], 0, s[98:99]
	global_store_dwordx4 v[182:183], v[176:179], off
	s_waitcnt vmcnt(15)
	v_lshlrev_b32_e32 v184, 16, v172
	v_and_b32_e32 v185, 0xffff0000, v172
	v_lshlrev_b32_e32 v186, 16, v173
	v_and_b32_e32 v187, 0xffff0000, v173
	v_pk_mul_f32 v[20:21], v[20:21], v[184:185]
	v_pk_mul_f32 v[22:23], v[22:23], v[186:187]
	v_lshlrev_b32_e32 v184, 16, v174
	v_and_b32_e32 v185, 0xffff0000, v174
	v_lshlrev_b32_e32 v186, 16, v175
	v_and_b32_e32 v187, 0xffff0000, v175
	v_pk_mul_f32 v[16:17], v[16:17], v[184:185]
	v_pk_mul_f32 v[18:19], v[18:19], v[186:187]
	v_cvt_pk_bf16_f32 v188, v20, v21
	v_cvt_pk_bf16_f32 v189, v22, v23
	v_cvt_pk_bf16_f32 v190, v16, v17
	v_cvt_pk_bf16_f32 v191, v18, v19
	global_store_dwordx4 v[182:183], v[188:191], off offset:256
	s_waitcnt vmcnt(14)
	v_lshlrev_b32_e32 v184, 16, v128
	v_and_b32_e32 v185, 0xffff0000, v128
	v_lshlrev_b32_e32 v186, 16, v129
	v_and_b32_e32 v187, 0xffff0000, v129
	v_pk_mul_f32 v[44:45], v[44:45], v[184:185]
	v_pk_mul_f32 v[46:47], v[46:47], v[186:187]
	v_lshlrev_b32_e32 v184, 16, v130
	v_and_b32_e32 v185, 0xffff0000, v130
	v_lshlrev_b32_e32 v186, 16, v131
	v_and_b32_e32 v187, 0xffff0000, v131
	v_pk_mul_f32 v[40:41], v[40:41], v[184:185]
	v_pk_mul_f32 v[42:43], v[42:43], v[186:187]
	v_cvt_pk_bf16_f32 v176, v44, v45
	v_cvt_pk_bf16_f32 v177, v46, v47
	v_cvt_pk_bf16_f32 v178, v40, v41
	v_cvt_pk_bf16_f32 v179, v42, v43
	s_mov_b32 s98, 0x50000
	s_mov_b32 s99, 0
	v_lshl_add_u64 v[182:183], v[216:217], 0, s[98:99]
	global_store_dwordx4 v[182:183], v[176:179], off
	s_waitcnt vmcnt(13)
	v_lshlrev_b32_e32 v184, 16, v132
	v_and_b32_e32 v185, 0xffff0000, v132
	v_lshlrev_b32_e32 v186, 16, v133
	v_and_b32_e32 v187, 0xffff0000, v133
	v_pk_mul_f32 v[12:13], v[12:13], v[184:185]
	v_pk_mul_f32 v[14:15], v[14:15], v[186:187]
	v_lshlrev_b32_e32 v184, 16, v134
	v_and_b32_e32 v185, 0xffff0000, v134
	v_lshlrev_b32_e32 v186, 16, v135
	v_and_b32_e32 v187, 0xffff0000, v135
	v_pk_mul_f32 v[8:9], v[8:9], v[184:185]
	v_pk_mul_f32 v[10:11], v[10:11], v[186:187]
	v_cvt_pk_bf16_f32 v188, v12, v13
	v_cvt_pk_bf16_f32 v189, v14, v15
	v_cvt_pk_bf16_f32 v190, v8, v9
	v_cvt_pk_bf16_f32 v191, v10, v11
	global_store_dwordx4 v[182:183], v[188:191], off offset:256
	s_waitcnt vmcnt(12)
	v_lshlrev_b32_e32 v184, 16, v136
	v_and_b32_e32 v185, 0xffff0000, v136
	v_lshlrev_b32_e32 v186, 16, v137
	v_and_b32_e32 v187, 0xffff0000, v137
	v_pk_mul_f32 v[36:37], v[36:37], v[184:185]
	v_pk_mul_f32 v[38:39], v[38:39], v[186:187]
	v_lshlrev_b32_e32 v184, 16, v138
	v_and_b32_e32 v185, 0xffff0000, v138
	v_lshlrev_b32_e32 v186, 16, v139
	v_and_b32_e32 v187, 0xffff0000, v139
	v_pk_mul_f32 v[32:33], v[32:33], v[184:185]
	v_pk_mul_f32 v[34:35], v[34:35], v[186:187]
	v_cvt_pk_bf16_f32 v176, v36, v37
	v_cvt_pk_bf16_f32 v177, v38, v39
	v_cvt_pk_bf16_f32 v178, v32, v33
	v_cvt_pk_bf16_f32 v179, v34, v35
	s_mov_b32 s98, 0x58000
	s_mov_b32 s99, 0
	v_lshl_add_u64 v[182:183], v[216:217], 0, s[98:99]
	global_store_dwordx4 v[182:183], v[176:179], off
	s_waitcnt vmcnt(11)
	v_lshlrev_b32_e32 v184, 16, v140
	v_and_b32_e32 v185, 0xffff0000, v140
	v_lshlrev_b32_e32 v186, 16, v141
	v_and_b32_e32 v187, 0xffff0000, v141
	v_pk_mul_f32 v[4:5], v[4:5], v[184:185]
	v_pk_mul_f32 v[6:7], v[6:7], v[186:187]
	v_lshlrev_b32_e32 v184, 16, v142
	v_and_b32_e32 v185, 0xffff0000, v142
	v_lshlrev_b32_e32 v186, 16, v143
	v_and_b32_e32 v187, 0xffff0000, v143
	v_pk_mul_f32 v[0:1], v[0:1], v[184:185]
	v_pk_mul_f32 v[2:3], v[2:3], v[186:187]
	v_cvt_pk_bf16_f32 v188, v4, v5
	v_cvt_pk_bf16_f32 v189, v6, v7
	v_cvt_pk_bf16_f32 v190, v0, v1
	v_cvt_pk_bf16_f32 v191, v2, v3
	global_store_dwordx4 v[182:183], v[188:191], off offset:256
	s_mov_b64 s[2:3], 0
.Lmg_done:
.LBB0_952:
	s_cmp_lg_u32 s5, 3
	s_mov_b64 s[22:23], -1
	s_cbranch_scc0 .LBB0_915
	s_and_b64 vcc, exec, s[2:3]
	s_cbranch_vccnz .LBB0_914
	v_mov_b32_e32 v0, 0
	v_mov_b64_e32 v[0:1], 0
	v_mov_b64_e32 v[2:3], 0
	v_mov_b64_e32 v[4:5], 0
	v_mov_b64_e32 v[6:7], 0
	v_mov_b64_e32 v[8:9], 0
	v_mov_b64_e32 v[10:11], 0
	v_mov_b64_e32 v[12:13], 0
	v_mov_b64_e32 v[14:15], 0
	v_mov_b64_e32 v[16:17], 0
	v_mov_b64_e32 v[18:19], 0
	v_mov_b64_e32 v[20:21], 0
	v_mov_b64_e32 v[22:23], 0
	v_mov_b64_e32 v[24:25], 0
	v_mov_b64_e32 v[26:27], 0
	v_mov_b64_e32 v[28:29], 0
	v_mov_b64_e32 v[30:31], 0
	v_mov_b64_e32 v[32:33], 0
	v_mov_b64_e32 v[34:35], 0
	v_mov_b64_e32 v[36:37], 0
	v_mov_b64_e32 v[38:39], 0
	v_mov_b64_e32 v[40:41], 0
	v_mov_b64_e32 v[42:43], 0
	v_mov_b64_e32 v[44:45], 0
	v_mov_b64_e32 v[46:47], 0
	v_mov_b64_e32 v[48:49], 0
	v_mov_b64_e32 v[50:51], 0
	v_mov_b64_e32 v[52:53], 0
	v_mov_b64_e32 v[54:55], 0
	v_mov_b64_e32 v[56:57], 0
	v_mov_b64_e32 v[58:59], 0
	v_mov_b64_e32 v[60:61], 0
	v_mov_b64_e32 v[62:63], 0
	v_mov_b64_e32 v[64:65], 0
	v_mov_b64_e32 v[66:67], 0
	v_mov_b64_e32 v[68:69], 0
	v_mov_b64_e32 v[70:71], 0
	v_mov_b64_e32 v[72:73], 0
	v_mov_b64_e32 v[74:75], 0
	v_mov_b64_e32 v[76:77], 0
	v_mov_b64_e32 v[78:79], 0
	v_mov_b64_e32 v[80:81], 0
	v_mov_b64_e32 v[82:83], 0
	v_mov_b64_e32 v[84:85], 0
	v_mov_b64_e32 v[86:87], 0
	v_mov_b64_e32 v[88:89], 0
	v_mov_b64_e32 v[90:91], 0
	v_mov_b64_e32 v[92:93], 0
	v_mov_b64_e32 v[94:95], 0
	v_mov_b64_e32 v[96:97], 0
	v_mov_b64_e32 v[98:99], 0
	v_mov_b64_e32 v[100:101], 0
	v_mov_b64_e32 v[102:103], 0
	v_mov_b64_e32 v[104:105], 0
	v_mov_b64_e32 v[106:107], 0
	v_mov_b64_e32 v[108:109], 0
	v_mov_b64_e32 v[110:111], 0
	v_mov_b64_e32 v[112:113], 0
	v_mov_b64_e32 v[114:115], 0
	v_mov_b64_e32 v[116:117], 0
	v_mov_b64_e32 v[118:119], 0
	v_mov_b64_e32 v[120:121], 0
	v_mov_b64_e32 v[122:123], 0
	v_mov_b64_e32 v[124:125], 0
	v_mov_b64_e32 v[126:127], 0
	s_branch .LBB0_914
